# itemwait: MIX1 chunk-state and RG-LRU item loops: loop-top waits on the back edge leave the previous item's (younger) stores in flight instead of also waiting for their acks; on top of xbpre
# speedup vs baseline: 1.0082x; 1.0082x over previous
.LBB0_421:
	s_add_i32 s35, s35, -1
	s_andn2_b64 vcc, exec, s[46:47]
	s_mov_b32 s51, s50
	v_readlane_b32 s52, v254, 55
	s_barrier
	s_cbranch_vccz .LBB0_432
	s_andn2_b64 vcc, exec, s[44:45]
	s_cbranch_vccnz .Lhl_full
	s_waitcnt vmcnt(4)
	s_branch .Lhl_body
.Lhl_full:
.LBB0_422:
	s_waitcnt vmcnt(0)
.Lhl_body:
	v_lshlrev_b32_e32 v2, 16, v18
	v_and_b32_e32 v3, 0xffff0000, v18
	s_add_i32 s50, s51, 1
	ds_write2_b32 v35, v2, v3 offset1:1
	v_lshlrev_b32_e32 v2, 16, v19
	v_and_b32_e32 v3, 0xffff0000, v19
	s_cmp_ge_i32 s50, s34
	ds_write2_b32 v35, v2, v3 offset0:2 offset1:3
	v_lshlrev_b32_e32 v2, 16, v20
	v_and_b32_e32 v3, 0xffff0000, v20
	s_cselect_b64 s[46:47], -1, 0
	ds_write2_b32 v35, v2, v3 offset0:4 offset1:5
	v_lshlrev_b32_e32 v2, 16, v21
	v_and_b32_e32 v3, 0xffff0000, v21
	s_and_b64 vcc, exec, s[46:47]
	ds_write2_b32 v35, v2, v3 offset0:6 offset1:7
	ds_write_b128 v36, v[22:25] offset:44544
	s_cbranch_vccnz .LBB0_428
	s_mul_hi_i32 s24, s50, 0x3e0f83e1
	s_lshr_b32 s25, s24, 31
	s_ashr_i32 s52, s24, 5
	s_add_i32 s52, s52, s25
	s_mul_i32 s24, s52, 0xffffff7c
	s_add_i32 s71, s51, s24
	s_add_i32 s61, s71, 1
	s_bfe_u32 s62, s52, 0x10002
	s_cmp_lt_u32 s52, 8
	s_mul_i32 s53, s52, 0x84
	s_cselect_b64 s[24:25], -1, 0
	s_cmp_gt_i32 s61, 3
	s_mov_b64 s[48:49], -1
	s_cbranch_scc0 .LBB0_425
	s_add_i32 s63, s35, s53
	s_add_i32 s71, s71, -3
	s_and_b64 s[48:49], s[24:25], exec
	s_cselect_b32 s70, s71, s63
	s_lshl_b32 s63, s62, 13
	s_mov_b64 s[48:49], 0

.LBB0_437:
	s_or_b64 exec, exec, s[4:5]
	s_waitcnt vmcnt(3)
	v_mul_f32_e32 v68, 0xbfb8aa3b, v68
	v_exp_f32_e32 v70, v68
	s_mov_b32 s4, 0x3f2aaaab
	s_mov_b32 s5, 0x3f317218
	s_mov_b32 s21, 0x7f800000
	v_add_f32_e32 v71, 1.0, v70
	v_add_f32_e32 v68, -1.0, v71
	v_sub_f32_e32 v69, v68, v71
	v_add_f32_e32 v69, 1.0, v69
	v_sub_f32_e32 v68, v70, v68
	v_add_f32_e32 v72, v68, v69
	v_frexp_mant_f32_e32 v73, v71
	v_cvt_f64_f32_e32 v[68:69], v71
	v_frexp_exp_i32_f64_e32 v68, v[68:69]
	v_cmp_gt_f32_e32 vcc, s4, v73
	s_waitcnt vmcnt(2)
	v_mul_f32_e32 v67, 0xbfb8aa3b, v67
	v_exp_f32_e32 v67, v67
	v_subbrev_co_u32_e32 v68, vcc, 0, v68, vcc
	v_sub_u32_e32 v69, 0, v68
	v_ldexp_f32 v71, v71, v69
	v_ldexp_f32 v69, v72, v69
	v_add_f32_e32 v72, -1.0, v71
	v_add_f32_e32 v75, 1.0, v71
	v_add_f32_e32 v73, 1.0, v72
	v_add_f32_e32 v76, -1.0, v75
	v_sub_f32_e32 v73, v71, v73
	v_sub_f32_e32 v71, v71, v76
	v_add_f32_e32 v73, v69, v73
	v_add_f32_e32 v69, v69, v71
	v_add_f32_e32 v71, v75, v69
	v_rcp_f32_e32 v76, v71
	v_add_f32_e32 v74, v72, v73
	v_sub_f32_e32 v72, v74, v72
	v_sub_f32_e32 v72, v73, v72
	v_sub_f32_e32 v73, v71, v75
	v_sub_f32_e32 v69, v69, v73
	v_mul_f32_e32 v73, v74, v76
	v_mul_f32_e32 v75, v71, v73
	v_fma_f32 v77, v73, v71, -v75
	v_fmac_f32_e32 v77, v73, v69
	v_add_f32_e32 v78, v75, v77
	v_sub_f32_e32 v79, v74, v78
	v_sub_f32_e32 v74, v74, v79
	v_sub_f32_e32 v75, v78, v75
	v_sub_f32_e32 v74, v74, v78
	v_add_f32_e32 v72, v72, v74
	v_sub_f32_e32 v74, v75, v77
	v_add_f32_e32 v72, v74, v72
	v_add_f32_e32 v74, v79, v72
	v_mul_f32_e32 v75, v76, v74
	v_mul_f32_e32 v77, v71, v75
	v_fma_f32 v71, v75, v71, -v77
	v_fmac_f32_e32 v71, v75, v69
	v_sub_f32_e32 v69, v79, v74
	v_add_f32_e32 v69, v72, v69
	v_add_f32_e32 v72, v77, v71
	v_sub_f32_e32 v78, v74, v72
	v_sub_f32_e32 v74, v74, v78
	v_sub_f32_e32 v77, v72, v77
	v_sub_f32_e32 v72, v74, v72
	v_add_f32_e32 v69, v69, v72
	v_sub_f32_e32 v71, v77, v71
	v_cvt_f32_i32_e32 v68, v68
	v_add_f32_e32 v69, v71, v69
	v_add_f32_e32 v71, v73, v75
	v_add_f32_e32 v69, v78, v69
	v_sub_f32_e32 v72, v71, v73
	v_mul_f32_e32 v69, v76, v69
	v_sub_f32_e32 v72, v75, v72
	v_add_f32_e32 v69, v72, v69
	v_mul_f32_e32 v75, 0x3f317218, v68
	v_add_f32_e32 v72, v71, v69
	v_fma_f32 v76, v68, s5, -v75
	v_mul_f32_e32 v73, v72, v72
	v_fmac_f32_e32 v76, 0xb102e308, v68
	v_sub_f32_e32 v68, v72, v71
	v_fmamk_f32 v74, v73, 0x3e9b6dac, v242
	v_sub_f32_e32 v68, v69, v68
	v_add_f32_e32 v69, v75, v76
	v_fmaak_f32 v74, v73, v74, 0x3f2aaada
	v_sub_f32_e32 v71, v69, v75
	v_ldexp_f32 v75, v72, 1
	v_mul_f32_e32 v72, v72, v73
	v_mul_f32_e32 v72, v72, v74
	v_add_f32_e32 v73, v75, v72
	v_sub_f32_e32 v74, v73, v75
	v_ldexp_f32 v68, v68, 1
	v_sub_f32_e32 v72, v72, v74
	v_add_f32_e32 v68, v68, v72
	v_add_f32_e32 v72, v73, v68
	v_sub_f32_e32 v73, v72, v73
	v_sub_f32_e32 v68, v68, v73
	v_add_f32_e32 v73, v69, v72
	v_sub_f32_e32 v74, v73, v69
	v_sub_f32_e32 v75, v73, v74
	v_sub_f32_e32 v71, v76, v71
	v_sub_f32_e32 v69, v69, v75
	v_sub_f32_e32 v72, v72, v74
	v_add_f32_e32 v69, v72, v69
	v_add_f32_e32 v72, v71, v68
	v_sub_f32_e32 v74, v72, v71
	v_sub_f32_e32 v75, v72, v74
	v_sub_f32_e32 v71, v71, v75
	v_sub_f32_e32 v68, v68, v74
	v_add_f32_e32 v69, v72, v69
	v_add_f32_e32 v68, v68, v71
	v_add_f32_e32 v71, v73, v69
	v_sub_f32_e32 v72, v71, v73
	v_sub_f32_e32 v69, v69, v72
	v_add_f32_e32 v68, v68, v69
	v_add_f32_e32 v68, v71, v68
	v_cmp_neq_f32_e32 vcc, s21, v70
	v_mov_b32_e32 v114, 0xff800000
	s_mov_b32 s22, 0x33800000
	v_cndmask_b32_e32 v68, v219, v68, vcc
	v_cmp_ngt_f32_e32 vcc, -1.0, v70
	s_waitcnt vmcnt(1)
	v_mul_f32_e32 v66, 0xbfb8aa3b, v66
	s_waitcnt vmcnt(0)
	v_mul_f32_e32 v0, 0xbfb8aa3b, v0
	v_cndmask_b32_e32 v68, v245, v68, vcc
	v_cmp_neq_f32_e32 vcc, -1.0, v70
	v_exp_f32_e32 v103, v0
	v_ashrrev_i32_e32 v131, 3, v98
	v_cndmask_b32_e32 v68, v114, v68, vcc
	v_cmp_lt_f32_e64 vcc, |v70|, s22
	v_lshlrev_b32_e32 v101, 4, v98
	v_and_b32_e32 v102, 0x70, v101
	v_cndmask_b32_e32 v132, v68, v70, vcc
	v_add_f32_e32 v70, 1.0, v67
	v_add_f32_e32 v68, -1.0, v70
	v_sub_f32_e32 v69, v68, v70
	v_add_f32_e32 v69, 1.0, v69
	v_sub_f32_e32 v68, v67, v68
	v_add_f32_e32 v71, v68, v69
	v_frexp_mant_f32_e32 v72, v70
	v_cvt_f64_f32_e32 v[68:69], v70
	v_frexp_exp_i32_f64_e32 v68, v[68:69]
	v_cmp_gt_f32_e32 vcc, s4, v72
	v_or_b32_e32 v104, s12, v102
	v_mov_b64_e32 v[90:91], s[82:83]
	v_subbrev_co_u32_e32 v68, vcc, 0, v68, vcc
	v_sub_u32_e32 v69, 0, v68
	v_ldexp_f32 v70, v70, v69
	v_ldexp_f32 v69, v71, v69
	v_add_f32_e32 v71, -1.0, v70
	v_add_f32_e32 v74, 1.0, v70
	v_add_f32_e32 v72, 1.0, v71
	v_add_f32_e32 v75, -1.0, v74
	v_sub_f32_e32 v72, v70, v72
	v_sub_f32_e32 v70, v70, v75
	v_add_f32_e32 v72, v69, v72
	v_add_f32_e32 v69, v69, v70
	v_add_f32_e32 v70, v74, v69
	v_rcp_f32_e32 v75, v70
	v_add_f32_e32 v73, v71, v72
	v_sub_f32_e32 v71, v73, v71
	v_sub_f32_e32 v71, v72, v71
	v_sub_f32_e32 v72, v70, v74
	v_sub_f32_e32 v69, v69, v72
	v_mul_f32_e32 v72, v73, v75
	v_mul_f32_e32 v74, v70, v72
	v_fma_f32 v76, v72, v70, -v74
	v_fmac_f32_e32 v76, v72, v69
	v_add_f32_e32 v77, v74, v76
	v_sub_f32_e32 v78, v73, v77
	v_sub_f32_e32 v73, v73, v78
	v_sub_f32_e32 v74, v77, v74
	v_sub_f32_e32 v73, v73, v77
	v_add_f32_e32 v71, v71, v73
	v_sub_f32_e32 v73, v74, v76
	v_add_f32_e32 v71, v73, v71
	v_add_f32_e32 v73, v78, v71
	v_mul_f32_e32 v74, v75, v73
	v_mul_f32_e32 v76, v70, v74
	v_fma_f32 v70, v74, v70, -v76
	v_fmac_f32_e32 v70, v74, v69
	v_sub_f32_e32 v69, v78, v73
	v_add_f32_e32 v69, v71, v69
	v_add_f32_e32 v71, v76, v70
	v_sub_f32_e32 v77, v73, v71
	v_sub_f32_e32 v73, v73, v77
	v_sub_f32_e32 v76, v71, v76
	v_sub_f32_e32 v71, v73, v71
	v_add_f32_e32 v69, v69, v71
	v_sub_f32_e32 v70, v76, v70
	v_cvt_f32_i32_e32 v68, v68
	v_add_f32_e32 v69, v70, v69
	v_add_f32_e32 v70, v72, v74
	v_add_f32_e32 v69, v77, v69
	v_sub_f32_e32 v71, v70, v72
	v_mul_f32_e32 v69, v75, v69
	v_sub_f32_e32 v71, v74, v71
	v_add_f32_e32 v69, v71, v69
	v_mul_f32_e32 v74, 0x3f317218, v68
	v_add_f32_e32 v71, v70, v69
	v_fma_f32 v75, v68, s5, -v74
	v_mul_f32_e32 v72, v71, v71
	v_fmac_f32_e32 v75, 0xb102e308, v68
	v_sub_f32_e32 v68, v71, v70
	v_fmamk_f32 v73, v72, 0x3e9b6dac, v242
	v_sub_f32_e32 v68, v69, v68
	v_add_f32_e32 v69, v74, v75
	v_fmaak_f32 v73, v72, v73, 0x3f2aaada
	v_sub_f32_e32 v70, v69, v74
	v_ldexp_f32 v74, v71, 1
	v_mul_f32_e32 v71, v71, v72
	v_mul_f32_e32 v71, v71, v73
	v_add_f32_e32 v72, v74, v71
	v_sub_f32_e32 v73, v72, v74
	v_ldexp_f32 v68, v68, 1
	v_sub_f32_e32 v71, v71, v73
	v_add_f32_e32 v68, v68, v71
	v_add_f32_e32 v71, v72, v68
	v_sub_f32_e32 v72, v71, v72
	v_sub_f32_e32 v68, v68, v72
	v_add_f32_e32 v72, v69, v71
	v_sub_f32_e32 v73, v72, v69
	v_sub_f32_e32 v74, v72, v73
	v_sub_f32_e32 v70, v75, v70
	v_sub_f32_e32 v69, v69, v74
	v_sub_f32_e32 v71, v71, v73
	v_add_f32_e32 v69, v71, v69
	v_add_f32_e32 v71, v70, v68
	v_sub_f32_e32 v73, v71, v70
	v_sub_f32_e32 v74, v71, v73
	v_sub_f32_e32 v70, v70, v74
	v_sub_f32_e32 v68, v68, v73
	v_add_f32_e32 v69, v71, v69
	v_add_f32_e32 v68, v68, v70
	v_add_f32_e32 v70, v72, v69
	v_sub_f32_e32 v71, v70, v72
	v_sub_f32_e32 v69, v69, v71
	v_add_f32_e32 v68, v68, v69
	v_exp_f32_e32 v69, v66
	v_add_f32_e32 v68, v70, v68
	v_cmp_neq_f32_e32 vcc, s21, v67
	s_mov_b64 s[24:25], 0x1000
	s_movk_i32 s20, 0x1000
	v_cndmask_b32_e32 v68, v219, v68, vcc
	v_cmp_ngt_f32_e32 vcc, -1.0, v67
	v_lshlrev_b32_e32 v137, 2, v99
	v_add_u32_e32 v148, 0, v101
	v_cndmask_b32_e32 v68, v245, v68, vcc
	v_cmp_neq_f32_e32 vcc, -1.0, v67
	v_lshl_add_u32 v120, v102, 1, 0
	v_mul_lo_u32 v121, v131, s88
	v_cndmask_b32_e32 v66, v114, v68, vcc
	v_cmp_lt_f32_e64 vcc, |v67|, s22
	v_add_f32_e32 v68, 1.0, v69
	v_frexp_mant_f32_e32 v71, v68
	v_cndmask_b32_e32 v133, v66, v67, vcc
	v_add_f32_e32 v66, -1.0, v68
	v_sub_f32_e32 v67, v66, v68
	v_add_f32_e32 v67, 1.0, v67
	v_sub_f32_e32 v66, v69, v66
	v_add_f32_e32 v70, v66, v67
	v_cvt_f64_f32_e32 v[66:67], v68
	v_frexp_exp_i32_f64_e32 v66, v[66:67]
	v_cmp_gt_f32_e32 vcc, s4, v71
	v_lshl_or_b32 v139, s14, 6, v137
	v_add_u32_e32 v149, 0xc400, v148
	v_subbrev_co_u32_e32 v66, vcc, 0, v66, vcc
	v_sub_u32_e32 v67, 0, v66
	v_ldexp_f32 v68, v68, v67
	v_ldexp_f32 v67, v70, v67
	v_add_f32_e32 v70, -1.0, v68
	v_add_f32_e32 v73, 1.0, v68
	v_add_f32_e32 v71, 1.0, v70
	v_add_f32_e32 v74, -1.0, v73
	v_sub_f32_e32 v71, v68, v71
	v_sub_f32_e32 v68, v68, v74
	v_add_f32_e32 v71, v67, v71
	v_add_f32_e32 v67, v67, v68
	v_add_f32_e32 v68, v73, v67
	v_rcp_f32_e32 v74, v68
	v_add_f32_e32 v72, v70, v71
	v_sub_f32_e32 v70, v72, v70
	v_sub_f32_e32 v70, v71, v70
	v_sub_f32_e32 v71, v68, v73
	v_sub_f32_e32 v67, v67, v71
	v_mul_f32_e32 v71, v72, v74
	v_mul_f32_e32 v73, v68, v71
	v_fma_f32 v75, v71, v68, -v73
	v_fmac_f32_e32 v75, v71, v67
	v_add_f32_e32 v76, v73, v75
	v_sub_f32_e32 v77, v72, v76
	v_sub_f32_e32 v72, v72, v77
	v_sub_f32_e32 v73, v76, v73
	v_sub_f32_e32 v72, v72, v76
	v_add_f32_e32 v70, v70, v72
	v_sub_f32_e32 v72, v73, v75
	v_add_f32_e32 v70, v72, v70
	v_add_f32_e32 v72, v77, v70
	v_mul_f32_e32 v73, v74, v72
	v_mul_f32_e32 v75, v68, v73
	v_fma_f32 v68, v73, v68, -v75
	v_fmac_f32_e32 v68, v73, v67
	v_sub_f32_e32 v67, v77, v72
	v_add_f32_e32 v67, v70, v67
	v_add_f32_e32 v70, v75, v68
	v_sub_f32_e32 v76, v72, v70
	v_sub_f32_e32 v72, v72, v76
	v_sub_f32_e32 v75, v70, v75
	v_sub_f32_e32 v70, v72, v70
	v_add_f32_e32 v67, v67, v70
	v_sub_f32_e32 v68, v75, v68
	v_cvt_f32_i32_e32 v66, v66
	v_add_f32_e32 v67, v68, v67
	v_add_f32_e32 v68, v71, v73
	v_add_f32_e32 v67, v76, v67
	v_sub_f32_e32 v70, v68, v71
	v_mul_f32_e32 v67, v74, v67
	v_sub_f32_e32 v70, v73, v70
	v_add_f32_e32 v67, v70, v67
	v_mul_f32_e32 v73, 0x3f317218, v66
	v_add_f32_e32 v70, v68, v67
	v_fma_f32 v74, v66, s5, -v73
	v_mul_f32_e32 v71, v70, v70
	v_fmac_f32_e32 v74, 0xb102e308, v66
	v_sub_f32_e32 v66, v70, v68
	v_fmamk_f32 v72, v71, 0x3e9b6dac, v242
	v_sub_f32_e32 v66, v67, v66
	v_add_f32_e32 v67, v73, v74
	v_fmaak_f32 v72, v71, v72, 0x3f2aaada
	v_sub_f32_e32 v68, v67, v73
	v_ldexp_f32 v73, v70, 1
	v_mul_f32_e32 v70, v70, v71
	v_mul_f32_e32 v70, v70, v72
	v_add_f32_e32 v71, v73, v70
	v_sub_f32_e32 v72, v71, v73
	v_ldexp_f32 v66, v66, 1
	v_sub_f32_e32 v70, v70, v72
	v_add_f32_e32 v66, v66, v70
	v_add_f32_e32 v70, v71, v66
	v_sub_f32_e32 v71, v70, v71
	v_sub_f32_e32 v66, v66, v71
	v_add_f32_e32 v71, v67, v70
	v_sub_f32_e32 v72, v71, v67
	v_sub_f32_e32 v73, v71, v72
	v_sub_f32_e32 v68, v74, v68
	v_sub_f32_e32 v67, v67, v73
	v_sub_f32_e32 v70, v70, v72
	v_add_f32_e32 v67, v70, v67
	v_add_f32_e32 v70, v68, v66
	v_sub_f32_e32 v72, v70, v68
	v_sub_f32_e32 v73, v70, v72
	v_sub_f32_e32 v68, v68, v73
	v_sub_f32_e32 v66, v66, v72
	v_add_f32_e32 v67, v70, v67
	v_add_f32_e32 v66, v66, v68
	v_add_f32_e32 v68, v71, v67
	v_sub_f32_e32 v70, v68, v71
	v_sub_f32_e32 v67, v67, v70
	v_add_f32_e32 v66, v66, v67
	v_add_f32_e32 v66, v68, v66
	v_cmp_neq_f32_e32 vcc, s21, v69
	v_add_u32_e32 v150, v120, v121
	v_lshlrev_b32_e32 v120, 1, v104
	v_cndmask_b32_e32 v66, v219, v66, vcc
	v_cmp_ngt_f32_e32 vcc, -1.0, v69
	s_nop 1
	v_cndmask_b32_e32 v66, v245, v66, vcc
	v_cmp_neq_f32_e32 vcc, -1.0, v69
	s_nop 1
	v_cndmask_b32_e32 v0, v114, v66, vcc
	v_cmp_lt_f32_e64 vcc, |v69|, s22
	s_nop 1
	v_cndmask_b32_e32 v134, v0, v69, vcc
	v_add_f32_e32 v0, 1.0, v103
	v_add_f32_e32 v66, -1.0, v0
	v_sub_f32_e32 v67, v66, v0
	v_add_f32_e32 v67, 1.0, v67
	v_sub_f32_e32 v66, v103, v66
	v_add_f32_e32 v68, v66, v67
	v_frexp_mant_f32_e32 v69, v0
	v_cvt_f64_f32_e32 v[66:67], v0
	v_frexp_exp_i32_f64_e32 v66, v[66:67]
	v_cmp_gt_f32_e32 vcc, s4, v69
	s_lshr_b32 s4, s16, 1
	s_nop 0
	v_subbrev_co_u32_e32 v66, vcc, 0, v66, vcc
	v_sub_u32_e32 v67, 0, v66
	v_ldexp_f32 v0, v0, v67
	v_ldexp_f32 v67, v68, v67
	v_add_f32_e32 v68, -1.0, v0
	v_add_f32_e32 v71, 1.0, v0
	v_add_f32_e32 v69, 1.0, v68
	v_add_f32_e32 v72, -1.0, v71
	v_sub_f32_e32 v69, v0, v69
	v_sub_f32_e32 v0, v0, v72
	v_add_f32_e32 v0, v67, v0
	v_add_f32_e32 v69, v67, v69
	v_add_f32_e32 v67, v71, v0
	v_rcp_f32_e32 v72, v67
	v_add_f32_e32 v70, v68, v69
	v_sub_f32_e32 v68, v70, v68
	v_sub_f32_e32 v68, v69, v68
	v_sub_f32_e32 v69, v67, v71
	v_sub_f32_e32 v0, v0, v69
	v_mul_f32_e32 v69, v70, v72
	v_mul_f32_e32 v71, v67, v69
	v_fma_f32 v73, v69, v67, -v71
	v_fmac_f32_e32 v73, v69, v0
	v_add_f32_e32 v74, v71, v73
	v_sub_f32_e32 v75, v70, v74
	v_sub_f32_e32 v70, v70, v75
	v_sub_f32_e32 v71, v74, v71
	v_sub_f32_e32 v70, v70, v74
	v_add_f32_e32 v68, v68, v70
	v_sub_f32_e32 v70, v71, v73
	v_add_f32_e32 v68, v70, v68
	v_add_f32_e32 v70, v75, v68
	v_mul_f32_e32 v71, v72, v70
	v_mul_f32_e32 v73, v67, v71
	v_fma_f32 v67, v71, v67, -v73
	v_fmac_f32_e32 v67, v71, v0
	v_sub_f32_e32 v0, v75, v70
	v_add_f32_e32 v0, v68, v0
	v_add_f32_e32 v68, v73, v67
	v_sub_f32_e32 v74, v70, v68
	v_sub_f32_e32 v70, v70, v74
	v_sub_f32_e32 v73, v68, v73
	v_sub_f32_e32 v68, v70, v68
	v_add_f32_e32 v0, v0, v68
	v_sub_f32_e32 v67, v73, v67
	v_cvt_f32_i32_e32 v66, v66
	v_add_f32_e32 v0, v67, v0
	v_add_f32_e32 v67, v69, v71
	v_add_f32_e32 v0, v74, v0
	v_sub_f32_e32 v68, v67, v69
	v_mul_f32_e32 v0, v72, v0
	v_sub_f32_e32 v68, v71, v68
	v_add_f32_e32 v0, v68, v0
	v_mul_f32_e32 v71, 0x3f317218, v66
	v_add_f32_e32 v68, v67, v0
	v_fma_f32 v72, v66, s5, -v71
	v_fmac_f32_e32 v72, 0xb102e308, v66
	v_sub_f32_e32 v66, v68, v67
	v_mul_f32_e32 v69, v68, v68
	v_sub_f32_e32 v0, v0, v66
	v_add_f32_e32 v66, v71, v72
	v_fmamk_f32 v70, v69, 0x3e9b6dac, v242
	v_sub_f32_e32 v67, v66, v71
	v_fmaak_f32 v70, v69, v70, 0x3f2aaada
	v_sub_f32_e32 v105, v72, v67
	v_ldexp_f32 v67, v68, 1
	v_mul_f32_e32 v68, v68, v69
	v_mul_f32_e32 v68, v68, v70
	s_add_i32 s5, s4, 0xffffff7c
	v_add_f32_e32 v69, v67, v68
	s_cmpk_lt_u32 s16, 0x108
	v_sub_f32_e32 v67, v69, v67
	s_cselect_b32 s4, s4, s5
	s_cmpk_gt_u32 s16, 0x107
	s_movk_i32 s5, 0x4100
	v_ldexp_f32 v0, v0, 1
	v_sub_f32_e32 v67, v68, v67
	s_cselect_b32 s5, s5, 0x4000
	s_cselect_b32 s6, 0x2000, 0
	s_lshl_b32 s7, s4, 6
	v_add_f32_e32 v0, v0, v67
	s_add_i32 s8, s7, 0xffffff00
	v_add_f32_e32 v67, v69, v0
	s_cmp_gt_u32 s4, 3
	s_movk_i32 s4, 0x100
	v_sub_f32_e32 v68, v67, v69
	v_add_f32_e32 v108, v66, v67
	s_cselect_b32 s17, 0x2000, s4
	s_cselect_b32 s4, s8, s7
	v_sub_f32_e32 v106, v0, v68
	v_sub_f32_e32 v0, v108, v66
	v_add_u32_e32 v111, s4, v131
	v_sub_f32_e32 v68, v108, v0
	v_sub_f32_e32 v110, v67, v0
	v_add_u32_e32 v0, -2, v111
	s_cselect_b32 s19, s6, s5
	v_cmp_lt_i32_e32 vcc, 1, v111
	v_cmp_gt_i32_e64 s[6:7], s17, v0
	s_and_b64 vcc, vcc, s[6:7]
	v_cndmask_b32_e32 v0, v111, v0, vcc
	v_add_u32_e32 v0, s19, v0
	v_sub_f32_e32 v109, v66, v68
	v_mad_i64_i32 v[66:67], s[4:5], v0, s85, v[90:91]
	v_lshlrev_b32_e32 v0, 1, v104
	v_lshl_add_u64 v[66:67], v[66:67], 0, v[0:1]
	v_lshl_add_u64 v[70:71], v[66:67], 0, s[24:25]
	v_add_co_u32_e64 v66, s[6:7], s20, v66
	v_cmp_ge_i32_e64 s[8:9], s17, v111
	s_nop 0
	v_addc_co_u32_e64 v67, s[6:7], 0, v67, s[6:7]
	v_cmp_lt_i32_e64 s[6:7], 0, v111
	v_add_u32_e32 v82, s19, v111
	s_and_b64 s[6:7], s[6:7], s[8:9]
	v_subbrev_co_u32_e64 v74, s[8:9], 0, v82, s[6:7]
	v_mad_i64_i32 v[74:75], s[4:5], v74, s85, v[90:91]
	v_lshl_add_u64 v[74:75], v[74:75], 0, v[0:1]
	v_lshl_add_u64 v[78:79], v[74:75], 0, s[24:25]
	v_add_co_u32_e64 v74, s[8:9], s20, v74
	v_mad_i64_i32 v[82:83], s[4:5], v82, s85, v[90:91]
	s_nop 0
	v_addc_co_u32_e64 v75, s[8:9], 0, v75, s[8:9]
	v_lshl_add_u64 v[82:83], v[82:83], 0, v[0:1]
	v_lshl_add_u64 v[86:87], v[82:83], 0, s[24:25]
	v_add_co_u32_e64 v82, s[8:9], s20, v82
	v_add_u32_e32 v92, 1, v111
	s_nop 0
	v_addc_co_u32_e64 v83, s[8:9], 0, v83, s[8:9]
	v_cmp_lt_i32_e64 s[8:9], -2, v111
	v_cmp_gt_i32_e64 s[10:11], s17, v92
	s_and_b64 s[8:9], s[8:9], s[10:11]
	v_cndmask_b32_e64 v92, v111, v92, s[8:9]
	v_add_u32_e32 v92, s19, v92
	v_mad_i64_i32 v[90:91], s[4:5], v92, s85, v[90:91]
	v_lshl_add_u64 v[90:91], v[90:91], 0, v[0:1]
	v_lshl_add_u64 v[94:95], v[90:91], 0, s[24:25]
	v_add_co_u32_e64 v90, s[10:11], s20, v90
	global_load_dwordx4 v[66:69], v[66:67], off
	s_nop 0
	global_load_dwordx4 v[70:73], v[70:71], off offset:16
	v_addc_co_u32_e64 v91, s[10:11], 0, v91, s[10:11]
	global_load_dwordx4 v[74:77], v[74:75], off
	s_nop 0
	global_load_dwordx4 v[78:81], v[78:79], off offset:16
	s_nop 0
	global_load_dwordx4 v[82:85], v[82:83], off
	s_nop 0
	global_load_dwordx4 v[86:89], v[86:87], off offset:16
	s_nop 0
	global_load_dwordx4 v[90:93], v[90:91], off
	s_nop 0
	global_load_dwordx4 v[94:97], v[94:95], off offset:16
	v_add_f32_e32 v0, v110, v109
	v_add_f32_e32 v109, v105, v106
	v_sub_f32_e32 v110, v109, v105
	v_sub_f32_e32 v112, v109, v110
	v_sub_f32_e32 v105, v105, v112
	v_sub_f32_e32 v106, v106, v110
	v_add_f32_e32 v0, v109, v0
	v_add_f32_e32 v105, v106, v105
	v_add_f32_e32 v106, v108, v0
	v_sub_f32_e32 v108, v106, v108
	v_sub_f32_e32 v0, v0, v108
	v_add_f32_e32 v0, v105, v0
	v_add_f32_e32 v0, v106, v0
	v_cmp_neq_f32_e64 s[10:11], s21, v103
	s_lshr_b32 s4, s13, 5
	s_and_b32 s19, s4, 2
	v_cndmask_b32_e64 v0, v219, v0, s[10:11]
	v_cmp_ngt_f32_e64 s[10:11], -1.0, v103
	s_lshl_b32 s4, s15, 7
	s_add_i32 s5, s4, 0
	v_cndmask_b32_e64 v0, v245, v0, s[10:11]
	v_cmp_neq_f32_e64 s[10:11], -1.0, v103
	v_lshl_add_u32 v136, v99, 4, s5
	v_bfe_u32 v99, v98, 7, 1
	v_cndmask_b32_e64 v0, v114, v0, s[10:11]
	v_cmp_lt_f32_e64 s[10:11], |v103|, s22
	v_cndmask_b32_e64 v112, 0, 1.0, s[6:7]
	v_cndmask_b32_e64 v122, 0, 1.0, s[8:9]
	v_cndmask_b32_e64 v135, v0, v103, s[10:11]
	v_lshlrev_b32_e32 v103, 1, v107
	v_add_u32_e32 v105, 0, v103
	v_add_u32_e32 v138, s4, v105
	s_lshl_b32 s4, s15, 8
	v_add3_u32 v140, v105, v103, s4
	v_mov_b32_e32 v103, 3
	v_lshlrev_b32_e32 v0, 2, v100
	v_or_b32_e32 v100, s12, v100
	s_movk_i32 s4, 0x80
	v_lshlrev_b32_sdwa v141, v103, v98 dst_sel:DWORD dst_unused:UNUSED_PAD src0_sel:DWORD src1_sel:BYTE_0
	v_lshlrev_b32_e32 v103, 15, v99
	v_cmp_lt_u32_sdwa s[6:7], v98, s4 src0_sel:BYTE_0 src1_sel:DWORD
	s_movk_i32 s4, 0x7f
	v_add3_u32 v142, 0, v0, v103
	v_lshlrev_b32_e32 v0, 3, v100
	v_cmp_gt_u32_sdwa s[12:13], v98, s4 src0_sel:BYTE_0 src1_sel:DWORD
	v_lshl_add_u64 v[108:109], s[96:97], 0, v[0:1]
	s_mov_b64 s[4:5], 0xf200000
	v_cmp_gt_u32_e64 s[8:9], s17, v111
	v_lshl_add_u64 v[108:109], v[108:109], 0, s[4:5]
	s_movk_i32 s4, 0xff
	v_cndmask_b32_e64 v124, 0, 1.0, s[8:9]
	v_cmp_lt_u32_e64 s[8:9], s4, v98
	v_lshlrev_b32_e32 v98, 2, v98
	v_add_u32_e32 v100, 0x800, v98
	v_lshlrev_b32_e32 v143, 1, v99
	v_ashrrev_i32_e32 v99, 31, v98
	v_ashrrev_i32_e32 v101, 31, v100
	v_lshlrev_b32_e32 v0, 2, v102
	v_readlane_b32 s5, v254, 10
	s_add_i32 s4, 0, 0x14400
	v_lshlrev_b64 v[110:111], 2, v[98:99]
	v_lshlrev_b64 v[114:115], 2, v[100:101]
	v_add_u32_e32 v100, 0x1000, v98
	v_add_u32_e32 v98, 0x1800, v98
	v_add_u32_e32 v144, s5, v0
	v_add_u32_e32 v145, s4, v0
	v_or_b32_e32 v0, 32, v0
	v_ashrrev_i32_e32 v101, 31, v100
	v_ashrrev_i32_e32 v99, 31, v98
	v_cndmask_b32_e64 v106, 0, 1.0, vcc
	v_add_u32_e32 v146, s5, v0
	v_add_u32_e32 v147, s4, v0
	v_lshlrev_b64 v[116:117], 2, v[100:101]
	v_lshlrev_b64 v[118:119], 2, v[98:99]
	s_waitcnt lgkmcnt(0)
	s_barrier
	s_mov_b32 s99, 0
	s_branch .LBB0_440

.LBB0_439:
	s_or_b64 exec, exec, s[10:11]
	s_lshl_b32 s10, s21, 1
	s_or_b32 s10, s10, s18
	s_ashr_i32 s11, s10, 31
	s_lshl_b64 s[10:11], s[10:11], 15
	s_add_u32 s16, s96, s10
	s_addc_u32 s17, s97, s11
	s_and_b64 s[10:11], s[4:5], exec
	s_waitcnt lgkmcnt(0)
	s_barrier
	ds_read_b128 v[98:101], v148 offset:17408
	ds_read_b128 v[226:229], v148 offset:25600
	ds_read_b128 v[230:233], v148 offset:33792
	ds_read_b128 v[234:237], v148 offset:41984
	s_mov_b32 s10, 0xe080000
	s_cselect_b32 s10, 0xe8c0000, s10
	s_add_u32 s10, s16, s10
	s_addc_u32 s11, s17, 0
	s_and_b64 s[4:5], s[4:5], exec
	s_cselect_b32 s4, 0x12000000, s73
	s_add_u32 s4, s16, s4
	s_addc_u32 s5, s17, 0
	s_and_b64 vcc, exec, s[14:15]
	s_mov_b32 s16, s20
	v_lshl_add_u64 v[102:103], s[10:11], 0, v[110:111]
	s_waitcnt lgkmcnt(3)
	global_store_dwordx4 v[102:103], v[98:101], off
	v_lshl_add_u64 v[220:221], s[10:11], 0, v[114:115]
	s_waitcnt lgkmcnt(2)
	global_store_dwordx4 v[220:221], v[226:229], off
	v_lshl_add_u64 v[102:103], s[10:11], 0, v[116:117]
	s_waitcnt lgkmcnt(1)
	global_store_dwordx4 v[102:103], v[230:233], off
	v_lshl_add_u64 v[220:221], s[10:11], 0, v[118:119]
	s_waitcnt lgkmcnt(0)
	global_store_dwordx4 v[220:221], v[234:237], off
	ds_read_b128 v[98:101], v148 offset:50176
	ds_read_b128 v[226:229], v148 offset:58368
	ds_read_b128 v[230:233], v149 offset:16384
	ds_read_b128 v[234:237], v149 offset:24576
	v_lshl_add_u64 v[102:103], s[4:5], 0, v[110:111]
	s_waitcnt lgkmcnt(3)
	global_store_dwordx4 v[102:103], v[98:101], off
	v_lshl_add_u64 v[220:221], s[4:5], 0, v[114:115]
	s_waitcnt lgkmcnt(2)
	global_store_dwordx4 v[220:221], v[226:229], off
	v_lshl_add_u64 v[102:103], s[4:5], 0, v[116:117]
	s_waitcnt lgkmcnt(1)
	global_store_dwordx4 v[102:103], v[230:233], off
	v_lshl_add_u64 v[220:221], s[4:5], 0, v[118:119]
	s_waitcnt lgkmcnt(0)
	global_store_dwordx4 v[220:221], v[234:237], off
	s_mov_b32 s99, 1
	s_cbranch_vccnz .LBB0_455
.LBB0_440:
	ds_read_b128 v[98:101], v145
	ds_read_b128 v[102:105], v144
	ds_read_b128 v[152:155], v144 offset:16
	ds_read_b128 v[156:159], v145 offset:16
	ds_read_b128 v[160:163], v145 offset:512
	s_waitcnt lgkmcnt(4)
	v_pk_mul_f32 v[164:165], v[106:107], v[100:101] op_sel_hi:[0,1]
	v_pk_mul_f32 v[166:167], v[106:107], v[98:99] op_sel_hi:[0,1]
	ds_read_b128 v[98:101], v145 offset:528
	v_mov_b32_e32 v170, v166
	s_waitcnt lgkmcnt(1)
	v_pk_mul_f32 v[160:161], v[112:113], v[160:161] op_sel_hi:[0,1]
	v_mov_b32_e32 v171, v160
	v_mov_b32_e32 v160, v167
	s_waitcnt lgkmcnt(0)
	v_pk_mul_f32 v[168:169], v[112:113], v[100:101] op_sel_hi:[0,1]
	s_cmp_eq_u32 s99, 0
	s_cbranch_scc1 .Lrgw_s0
	s_waitcnt vmcnt(13)
	s_branch .Lrgw_j0
.Lrgw_s0:
	s_waitcnt vmcnt(5)
.Lrgw_j0:
	v_lshlrev_b32_e32 v101, 16, v74
	v_lshlrev_b32_e32 v100, 16, v66
	v_pk_mul_f32 v[100:101], v[170:171], v[100:101]
	v_pk_mul_f32 v[162:163], v[112:113], v[162:163] op_sel_hi:[0,1]
	v_add_f32_e32 v0, v102, v100
	v_add_f32_e32 v0, v0, v101
	v_and_b32_e32 v101, 0xffff0000, v74
	v_and_b32_e32 v100, 0xffff0000, v66
	v_pk_mul_f32 v[100:101], v[160:161], v[100:101]
	v_mov_b32_e32 v102, v164
	v_add_f32_e32 v100, v103, v100
	v_add_f32_e32 v121, v100, v101
	v_lshlrev_b32_e32 v101, 16, v75
	v_lshlrev_b32_e32 v100, 16, v67
	v_mov_b32_e32 v103, v162
	v_pk_mul_f32 v[100:101], v[102:103], v[100:101]
	v_mov_b32_e32 v162, v165
	v_add_f32_e32 v100, v104, v100
	v_add_f32_e32 v151, v100, v101
	v_and_b32_e32 v101, 0xffff0000, v75
	v_and_b32_e32 v100, 0xffff0000, v67
	v_pk_mul_f32 v[100:101], v[162:163], v[100:101]
	v_pk_mul_f32 v[156:157], v[106:107], v[156:157] op_sel_hi:[0,1]
	v_pk_mul_f32 v[98:99], v[112:113], v[98:99] op_sel_hi:[0,1]
	v_add_f32_e32 v100, v105, v100
	v_add_f32_e32 v164, v100, v101
	v_lshlrev_b32_e32 v101, 16, v76
	v_lshlrev_b32_e32 v100, 16, v68
	v_mov_b32_e32 v102, v156
	v_mov_b32_e32 v103, v98
	v_pk_mul_f32 v[100:101], v[102:103], v[100:101]
	v_pk_mul_f32 v[158:159], v[106:107], v[158:159] op_sel_hi:[0,1]
	v_add_f32_e32 v98, v152, v100
	v_add_f32_e32 v165, v98, v101
	v_and_b32_e32 v101, 0xffff0000, v76
	v_and_b32_e32 v100, 0xffff0000, v68
	v_mov_b32_e32 v98, v157
	v_pk_mul_f32 v[98:99], v[98:99], v[100:101]
	v_mov_b32_e32 v100, v158
	v_add_f32_e32 v98, v153, v98
	v_add_f32_e32 v166, v98, v99
	v_lshlrev_b32_e32 v99, 16, v77
	v_lshlrev_b32_e32 v98, 16, v69
	v_mov_b32_e32 v101, v168
	v_pk_mul_f32 v[98:99], v[100:101], v[98:99]
	v_and_b32_e32 v103, 0xffff0000, v77
	v_and_b32_e32 v102, 0xffff0000, v69
	v_mov_b32_e32 v168, v159
	v_add_f32_e32 v98, v154, v98
	v_pk_mul_f32 v[102:103], v[168:169], v[102:103]
	v_add_f32_e32 v167, v98, v99
	ds_read_b128 v[98:101], v145 offset:1024
	v_add_f32_e32 v102, v155, v102
	ds_read_b128 v[152:155], v145 offset:1536
	v_add_f32_e32 v168, v102, v103
	ds_read_b128 v[102:105], v145 offset:1040
	s_waitcnt lgkmcnt(2)
	v_pk_mul_f32 v[156:157], v[124:125], v[100:101] op_sel_hi:[0,1]
	v_pk_mul_f32 v[158:159], v[124:125], v[98:99] op_sel_hi:[0,1]
	ds_read_b128 v[98:101], v145 offset:1552
	s_waitcnt lgkmcnt(2)
	v_pk_mul_f32 v[152:153], v[122:123], v[152:153] op_sel_hi:[0,1]
	s_cmp_eq_u32 s99, 0
	s_cbranch_scc1 .Lrgw_s1
	s_waitcnt vmcnt(9)
	s_branch .Lrgw_j1
.Lrgw_s1:
	s_waitcnt vmcnt(1)
.Lrgw_j1:
	v_lshlrev_b32_e32 v161, 16, v90
	v_lshlrev_b32_e32 v160, 16, v82
	v_mov_b32_e32 v162, v158
	v_mov_b32_e32 v163, v152
	v_pk_mul_f32 v[160:161], v[162:163], v[160:161]
	v_mov_b32_e32 v152, v159
	v_add_f32_e32 v0, v0, v160
	v_add_f32_e32 v0, v0, v161
	v_and_b32_e32 v161, 0xffff0000, v90
	v_and_b32_e32 v160, 0xffff0000, v82
	v_pk_mul_f32 v[152:153], v[152:153], v[160:161]
	v_pk_mul_f32 v[154:155], v[122:123], v[154:155] op_sel_hi:[0,1]
	v_add_f32_e32 v121, v121, v152
	v_add_f32_e32 v121, v121, v153
	v_lshlrev_b32_e32 v153, 16, v91
	v_lshlrev_b32_e32 v152, 16, v83
	v_mov_b32_e32 v158, v156
	v_mov_b32_e32 v159, v154
	v_pk_mul_f32 v[152:153], v[158:159], v[152:153]
	v_mov_b32_e32 v154, v157
	v_add_f32_e32 v151, v151, v152
	v_add_f32_e32 v151, v151, v153
	v_and_b32_e32 v153, 0xffff0000, v91
	v_and_b32_e32 v152, 0xffff0000, v83
	v_pk_mul_f32 v[152:153], v[154:155], v[152:153]
	s_waitcnt lgkmcnt(1)
	v_pk_mul_f32 v[102:103], v[124:125], v[102:103] op_sel_hi:[0,1]
	s_waitcnt lgkmcnt(0)
	v_pk_mul_f32 v[98:99], v[122:123], v[98:99] op_sel_hi:[0,1]
	v_add_f32_e32 v152, v164, v152
	v_add_f32_e32 v156, v152, v153
	v_lshlrev_b32_e32 v153, 16, v92
	v_lshlrev_b32_e32 v152, 16, v84
	v_mov_b32_e32 v154, v102
	v_mov_b32_e32 v155, v98
	v_pk_mul_f32 v[152:153], v[154:155], v[152:153]
	v_pk_mul_f32 v[104:105], v[124:125], v[104:105] op_sel_hi:[0,1]
	v_add_f32_e32 v98, v165, v152
	v_add_f32_e32 v154, v98, v153
	v_and_b32_e32 v153, 0xffff0000, v92
	v_and_b32_e32 v152, 0xffff0000, v84
	v_mov_b32_e32 v98, v103
	v_pk_mul_f32 v[98:99], v[98:99], v[152:153]
	v_pk_mul_f32 v[100:101], v[122:123], v[100:101] op_sel_hi:[0,1]
	v_add_f32_e32 v98, v166, v98
	v_add_f32_e32 v152, v98, v99
	v_lshlrev_b32_e32 v99, 16, v93
	v_lshlrev_b32_e32 v98, 16, v85
	v_mov_b32_e32 v102, v104
	v_mov_b32_e32 v103, v100
	v_pk_mul_f32 v[98:99], v[102:103], v[98:99]
	v_mov_b32_e32 v100, v105
	v_add_f32_e32 v98, v167, v98
	v_add_f32_e32 v102, v98, v99
	v_and_b32_e32 v99, 0xffff0000, v93
	v_and_b32_e32 v98, 0xffff0000, v85
	v_pk_mul_f32 v[98:99], v[100:101], v[98:99]
	s_add_i32 s20, s16, 0xbe
	v_add_f32_e32 v98, v168, v98
	v_add_f32_e32 v101, v98, v99
	v_cvt_pk_bf16_f32 v98, v0, v121
	v_cvt_pk_bf16_f32 v99, v151, v156
	v_cvt_pk_bf16_f32 v100, v154, v152
	v_cvt_pk_bf16_f32 v101, v102, v101
	ds_write_b128 v150, v[98:101]
	ds_read_b128 v[98:101], v147
	ds_read_b128 v[102:105], v146
	ds_read_b128 v[152:155], v146 offset:16
	ds_read_b128 v[156:159], v147 offset:16
	ds_read_b128 v[160:163], v147 offset:512
	s_waitcnt lgkmcnt(4)
	v_pk_mul_f32 v[164:165], v[106:107], v[100:101] op_sel_hi:[0,1]
	v_pk_mul_f32 v[166:167], v[106:107], v[98:99] op_sel_hi:[0,1]
	ds_read_b128 v[98:101], v147 offset:528
	v_mov_b32_e32 v170, v166
	s_waitcnt lgkmcnt(1)
	v_pk_mul_f32 v[160:161], v[112:113], v[160:161] op_sel_hi:[0,1]
	v_mov_b32_e32 v171, v160
	v_mov_b32_e32 v160, v167
	s_waitcnt lgkmcnt(0)
	v_pk_mul_f32 v[168:169], v[112:113], v[100:101] op_sel_hi:[0,1]
	v_lshlrev_b32_e32 v101, 16, v78
	v_lshlrev_b32_e32 v100, 16, v70
	v_pk_mul_f32 v[100:101], v[170:171], v[100:101]
	v_pk_mul_f32 v[162:163], v[112:113], v[162:163] op_sel_hi:[0,1]
	v_add_f32_e32 v0, v102, v100
	v_add_f32_e32 v0, v0, v101
	v_and_b32_e32 v101, 0xffff0000, v78
	v_and_b32_e32 v100, 0xffff0000, v70
	v_pk_mul_f32 v[100:101], v[160:161], v[100:101]
	v_mov_b32_e32 v102, v164
	v_add_f32_e32 v100, v103, v100
	v_add_f32_e32 v121, v100, v101
	v_lshlrev_b32_e32 v101, 16, v79
	v_lshlrev_b32_e32 v100, 16, v71
	v_mov_b32_e32 v103, v162
	v_pk_mul_f32 v[100:101], v[102:103], v[100:101]
	v_mov_b32_e32 v162, v165
	v_add_f32_e32 v100, v104, v100
	v_add_f32_e32 v151, v100, v101
	v_and_b32_e32 v101, 0xffff0000, v79
	v_and_b32_e32 v100, 0xffff0000, v71
	v_pk_mul_f32 v[100:101], v[162:163], v[100:101]
	v_pk_mul_f32 v[156:157], v[106:107], v[156:157] op_sel_hi:[0,1]
	v_pk_mul_f32 v[98:99], v[112:113], v[98:99] op_sel_hi:[0,1]
	v_add_f32_e32 v100, v105, v100
	v_add_f32_e32 v164, v100, v101
	v_lshlrev_b32_e32 v101, 16, v80
	v_lshlrev_b32_e32 v100, 16, v72
	v_mov_b32_e32 v102, v156
	v_mov_b32_e32 v103, v98
	v_pk_mul_f32 v[100:101], v[102:103], v[100:101]
	v_pk_mul_f32 v[158:159], v[106:107], v[158:159] op_sel_hi:[0,1]
	v_add_f32_e32 v98, v152, v100
	v_add_f32_e32 v165, v98, v101
	v_and_b32_e32 v101, 0xffff0000, v80
	v_and_b32_e32 v100, 0xffff0000, v72
	v_mov_b32_e32 v98, v157
	v_pk_mul_f32 v[98:99], v[98:99], v[100:101]
	v_mov_b32_e32 v100, v158
	v_add_f32_e32 v98, v153, v98
	v_add_f32_e32 v166, v98, v99
	v_lshlrev_b32_e32 v99, 16, v81
	v_lshlrev_b32_e32 v98, 16, v73
	v_mov_b32_e32 v101, v168
	v_pk_mul_f32 v[98:99], v[100:101], v[98:99]
	v_and_b32_e32 v103, 0xffff0000, v81
	v_and_b32_e32 v102, 0xffff0000, v73
	v_mov_b32_e32 v168, v159
	v_add_f32_e32 v98, v154, v98
	v_pk_mul_f32 v[102:103], v[168:169], v[102:103]
	v_add_f32_e32 v167, v98, v99
	ds_read_b128 v[98:101], v147 offset:1024
	v_add_f32_e32 v102, v155, v102
	ds_read_b128 v[152:155], v147 offset:1536
	v_add_f32_e32 v168, v102, v103
	ds_read_b128 v[102:105], v147 offset:1040
	s_waitcnt lgkmcnt(2)
	v_pk_mul_f32 v[156:157], v[124:125], v[100:101] op_sel_hi:[0,1]
	v_pk_mul_f32 v[158:159], v[124:125], v[98:99] op_sel_hi:[0,1]
	ds_read_b128 v[98:101], v147 offset:1552
	s_waitcnt lgkmcnt(2)
	v_pk_mul_f32 v[152:153], v[122:123], v[152:153] op_sel_hi:[0,1]
	s_cmp_eq_u32 s99, 0
	s_cbranch_scc1 .Lrgw_s2
	s_waitcnt vmcnt(8)
	s_branch .Lrgw_j2

.Lrgw_j2:
	v_lshlrev_b32_e32 v161, 16, v94
	v_lshlrev_b32_e32 v160, 16, v86
	v_mov_b32_e32 v162, v158
	v_mov_b32_e32 v163, v152
	v_pk_mul_f32 v[160:161], v[162:163], v[160:161]
	v_mov_b32_e32 v152, v159
	v_add_f32_e32 v0, v0, v160
	v_add_f32_e32 v0, v0, v161
	v_and_b32_e32 v161, 0xffff0000, v94
	v_and_b32_e32 v160, 0xffff0000, v86
	v_pk_mul_f32 v[152:153], v[152:153], v[160:161]
	v_pk_mul_f32 v[154:155], v[122:123], v[154:155] op_sel_hi:[0,1]
	v_add_f32_e32 v121, v121, v152
	v_add_f32_e32 v121, v121, v153
	v_lshlrev_b32_e32 v153, 16, v95
	v_lshlrev_b32_e32 v152, 16, v87
	v_mov_b32_e32 v158, v156
	v_mov_b32_e32 v159, v154
	v_pk_mul_f32 v[152:153], v[158:159], v[152:153]
	v_mov_b32_e32 v154, v157
	v_add_f32_e32 v151, v151, v152
	v_add_f32_e32 v151, v151, v153
	v_and_b32_e32 v153, 0xffff0000, v95
	v_and_b32_e32 v152, 0xffff0000, v87
	v_pk_mul_f32 v[152:153], v[154:155], v[152:153]
	s_waitcnt lgkmcnt(1)
	v_pk_mul_f32 v[102:103], v[124:125], v[102:103] op_sel_hi:[0,1]
	s_waitcnt lgkmcnt(0)
	v_pk_mul_f32 v[98:99], v[122:123], v[98:99] op_sel_hi:[0,1]
	v_add_f32_e32 v152, v164, v152
	v_add_f32_e32 v156, v152, v153
	v_lshlrev_b32_e32 v153, 16, v96
	v_lshlrev_b32_e32 v152, 16, v88
	v_mov_b32_e32 v154, v102
	v_mov_b32_e32 v155, v98
	v_pk_mul_f32 v[152:153], v[154:155], v[152:153]
	v_pk_mul_f32 v[104:105], v[124:125], v[104:105] op_sel_hi:[0,1]
	v_add_f32_e32 v98, v165, v152
	v_add_f32_e32 v154, v98, v153
	v_and_b32_e32 v153, 0xffff0000, v96
	v_and_b32_e32 v152, 0xffff0000, v88
	v_mov_b32_e32 v98, v103
	v_pk_mul_f32 v[98:99], v[98:99], v[152:153]
	v_pk_mul_f32 v[100:101], v[122:123], v[100:101] op_sel_hi:[0,1]
	v_add_f32_e32 v98, v166, v98
	v_add_f32_e32 v152, v98, v99
	v_lshlrev_b32_e32 v99, 16, v97
	v_lshlrev_b32_e32 v98, 16, v89
	v_mov_b32_e32 v102, v104
	v_mov_b32_e32 v103, v100
	v_pk_mul_f32 v[98:99], v[102:103], v[98:99]
	v_mov_b32_e32 v100, v105
	v_add_f32_e32 v98, v167, v98
	v_add_f32_e32 v102, v98, v99
	v_and_b32_e32 v99, 0xffff0000, v97
	v_and_b32_e32 v98, 0xffff0000, v89
	v_pk_mul_f32 v[98:99], v[100:101], v[98:99]
	s_cmpk_gt_u32 s16, 0x151
	v_add_f32_e32 v98, v168, v98
	s_cselect_b64 s[14:15], -1, 0
	v_add_f32_e32 v101, v98, v99
	s_and_b64 vcc, exec, s[14:15]
	v_cvt_pk_bf16_f32 v98, v0, v121
	v_cvt_pk_bf16_f32 v99, v151, v156
	v_cvt_pk_bf16_f32 v100, v154, v152
	v_cvt_pk_bf16_f32 v101, v102, v101
	ds_write_b128 v150, v[98:101] offset:16
	s_cbranch_vccnz .LBB0_442
	s_lshr_b32 s4, s20, 1
	s_add_i32 s5, s4, 0xffffff7c
	s_cmpk_lt_u32 s16, 0x4a
	s_cselect_b32 s4, s4, s5
	s_cmpk_gt_u32 s16, 0x49
	s_movk_i32 s5, 0x4100
	s_cselect_b32 s5, s5, 0x4000
	s_cselect_b32 s10, 0x2000, 0
	s_lshl_b32 s11, s4, 6
	s_add_i32 s17, s11, 0xffffff00
	s_cmp_gt_u32 s4, 3
	s_movk_i32 s4, 0x100
	s_cselect_b32 s21, 0x2000, s4
	s_cselect_b32 s4, s17, s11
	v_add_u32_e32 v0, s4, v131
	v_add_u32_e32 v66, -2, v0
	s_cselect_b32 s22, s10, s5
	v_cmp_lt_i32_e32 vcc, 1, v0
	v_cmp_gt_i32_e64 s[10:11], s21, v66
	s_and_b64 vcc, vcc, s[10:11]
	v_cndmask_b32_e32 v66, v0, v66, vcc
	v_add_u32_e32 v66, s22, v66
	v_mov_b64_e32 v[90:91], s[82:83]
	v_mad_i64_i32 v[66:67], s[4:5], v66, s85, v[90:91]
	v_mov_b32_e32 v121, v1
	v_lshl_add_u64 v[66:67], v[66:67], 0, v[120:121]
	s_mov_b64 s[24:25], 0x1000
	s_movk_i32 s17, 0x1000
	v_cndmask_b32_e64 v106, 0, 1.0, vcc
	v_lshl_add_u64 v[70:71], v[66:67], 0, s[24:25]
	v_add_co_u32_e32 v66, vcc, s17, v66
	v_cmp_ge_i32_e64 s[10:11], s21, v0
	s_nop 0
	v_addc_co_u32_e32 v67, vcc, 0, v67, vcc
	v_cmp_lt_i32_e32 vcc, 0, v0
	s_and_b64 vcc, vcc, s[10:11]
	v_add_u32_e32 v82, s22, v0
	v_cndmask_b32_e64 v112, 0, 1.0, vcc
	v_subbrev_co_u32_e32 v74, vcc, 0, v82, vcc
	v_mad_i64_i32 v[74:75], s[4:5], v74, s85, v[90:91]
	v_lshl_add_u64 v[74:75], v[74:75], 0, v[120:121]
	v_lshl_add_u64 v[78:79], v[74:75], 0, s[24:25]
	v_add_co_u32_e32 v74, vcc, s17, v74
	v_mad_i64_i32 v[82:83], s[4:5], v82, s85, v[90:91]
	s_nop 0
	v_addc_co_u32_e32 v75, vcc, 0, v75, vcc
	v_lshl_add_u64 v[82:83], v[82:83], 0, v[120:121]
	v_lshl_add_u64 v[86:87], v[82:83], 0, s[24:25]
	v_add_co_u32_e32 v82, vcc, s17, v82
	v_add_u32_e32 v92, 1, v0
	s_nop 0
	v_addc_co_u32_e32 v83, vcc, 0, v83, vcc
	v_cmp_lt_i32_e32 vcc, -2, v0
	v_cmp_gt_i32_e64 s[10:11], s21, v92
	s_and_b64 vcc, vcc, s[10:11]
	v_cndmask_b32_e32 v92, v0, v92, vcc
	v_add_u32_e32 v92, s22, v92
	v_mad_i64_i32 v[90:91], s[4:5], v92, s85, v[90:91]
	v_lshl_add_u64 v[90:91], v[90:91], 0, v[120:121]
	v_cndmask_b32_e64 v122, 0, 1.0, vcc
	v_lshl_add_u64 v[94:95], v[90:91], 0, s[24:25]
	v_add_co_u32_e32 v90, vcc, 0x1000, v90
	global_load_dwordx4 v[66:69], v[66:67], off
	s_nop 0
	global_load_dwordx4 v[70:73], v[70:71], off offset:16
	v_addc_co_u32_e32 v91, vcc, 0, v91, vcc
	global_load_dwordx4 v[74:77], v[74:75], off
	s_nop 0
	global_load_dwordx4 v[78:81], v[78:79], off offset:16
	s_nop 0
	global_load_dwordx4 v[82:85], v[82:83], off
	s_nop 0
	global_load_dwordx4 v[86:89], v[86:87], off offset:16
	s_nop 0
	global_load_dwordx4 v[90:93], v[90:91], off
	s_nop 0
	global_load_dwordx4 v[94:97], v[94:95], off offset:16
	v_cmp_gt_u32_e32 vcc, s21, v0
	s_nop 1
	v_cndmask_b32_e64 v124, 0, 1.0, vcc
